# residual-add GEMM epilogues as a pipelined load ring with counted vmcnt instead of the load-wait-add-store ladder
# baseline (speedup 1.0000x reference)
.LBB0_863:
	v_lshl_add_u32 v140, s46, 8, v142
	v_lshl_or_b32 v138, s69, 8, v144
	v_lshlrev_b32_e32 v157, 2, v138
	v_lshl_add_u32 v156, v140, 12, v157
	s_mov_b64 s[48:49], s[14:15]
	s_mov_b64 s[50:51], s[14:15]
	s_mov_b64 s[4:5], -1
	s_andn2_b64 vcc, exec, s[8:9]
	global_load_dwordx4 v[158:161], v156, s[48:49]
	global_load_dwordx4 v[162:165], v156, s[48:49] offset:16
	global_load_dwordx4 v[166:169], v156, s[48:49] offset:512
	global_load_dwordx4 v[170:173], v156, s[48:49] offset:528
	s_add_u32 s48, s48, 0x10000
	s_addc_u32 s49, s49, 0
	global_load_dwordx4 v[174:177], v156, s[48:49]
	global_load_dwordx4 v[178:181], v156, s[48:49] offset:16
	global_load_dwordx4 v[182:185], v156, s[48:49] offset:512
	global_load_dwordx4 v[186:189], v156, s[48:49] offset:528
	s_add_u32 s48, s48, 0x10000
	s_addc_u32 s49, s49, 0
	global_load_dwordx4 v[190:193], v156, s[48:49]
	global_load_dwordx4 v[194:197], v156, s[48:49] offset:16
	global_load_dwordx4 v[198:201], v156, s[48:49] offset:512
	global_load_dwordx4 v[202:205], v156, s[48:49] offset:528
	s_waitcnt vmcnt(10)
	v_pk_add_f32 v[124:125], v[124:125], v[158:159]
	v_pk_add_f32 v[126:127], v[126:127], v[160:161]
	v_pk_add_f32 v[120:121], v[120:121], v[162:163]
	v_pk_add_f32 v[122:123], v[122:123], v[164:165]
	global_store_dwordx4 v156, v[124:127], s[50:51]
	global_store_dwordx4 v156, v[120:123], s[50:51] offset:16
	s_add_u32 s48, s48, 0x10000
	s_addc_u32 s49, s49, 0
	global_load_dwordx4 v[158:161], v156, s[48:49]
	global_load_dwordx4 v[162:165], v156, s[48:49] offset:16
	s_waitcnt vmcnt(12)
	v_pk_add_f32 v[116:117], v[116:117], v[166:167]
	v_pk_add_f32 v[118:119], v[118:119], v[168:169]
	v_pk_add_f32 v[112:113], v[112:113], v[170:171]
	v_pk_add_f32 v[114:115], v[114:115], v[172:173]
	global_store_dwordx4 v156, v[116:119], s[50:51] offset:512
	global_store_dwordx4 v156, v[112:115], s[50:51] offset:528
	global_load_dwordx4 v[166:169], v156, s[48:49] offset:512
	global_load_dwordx4 v[170:173], v156, s[48:49] offset:528
	s_waitcnt vmcnt(14)
	v_pk_add_f32 v[108:109], v[108:109], v[174:175]
	v_pk_add_f32 v[110:111], v[110:111], v[176:177]
	v_pk_add_f32 v[104:105], v[104:105], v[178:179]
	v_pk_add_f32 v[106:107], v[106:107], v[180:181]
	s_add_u32 s50, s50, 0x10000
	s_addc_u32 s51, s51, 0
	global_store_dwordx4 v156, v[108:111], s[50:51]
	global_store_dwordx4 v156, v[104:107], s[50:51] offset:16
	s_add_u32 s48, s48, 0x50000
	s_addc_u32 s49, s49, 0
	global_load_dwordx4 v[174:177], v156, s[48:49]
	global_load_dwordx4 v[178:181], v156, s[48:49] offset:16
	s_waitcnt vmcnt(16)
	v_pk_add_f32 v[100:101], v[100:101], v[182:183]
	v_pk_add_f32 v[102:103], v[102:103], v[184:185]
	v_pk_add_f32 v[96:97], v[96:97], v[186:187]
	v_pk_add_f32 v[98:99], v[98:99], v[188:189]
	global_store_dwordx4 v156, v[100:103], s[50:51] offset:512
	global_store_dwordx4 v156, v[96:99], s[50:51] offset:528
	global_load_dwordx4 v[182:185], v156, s[48:49] offset:512
	global_load_dwordx4 v[186:189], v156, s[48:49] offset:528
	s_waitcnt vmcnt(18)
	v_pk_add_f32 v[92:93], v[92:93], v[190:191]
	v_pk_add_f32 v[94:95], v[94:95], v[192:193]
	v_pk_add_f32 v[88:89], v[88:89], v[194:195]
	v_pk_add_f32 v[90:91], v[90:91], v[196:197]
	s_add_u32 s50, s50, 0x10000
	s_addc_u32 s51, s51, 0
	global_store_dwordx4 v156, v[92:95], s[50:51]
	global_store_dwordx4 v156, v[88:91], s[50:51] offset:16
	s_add_u32 s48, s48, 0x10000
	s_addc_u32 s49, s49, 0
	global_load_dwordx4 v[190:193], v156, s[48:49]
	global_load_dwordx4 v[194:197], v156, s[48:49] offset:16
	s_waitcnt vmcnt(20)
	v_pk_add_f32 v[84:85], v[84:85], v[198:199]
	v_pk_add_f32 v[86:87], v[86:87], v[200:201]
	v_pk_add_f32 v[80:81], v[80:81], v[202:203]
	v_pk_add_f32 v[82:83], v[82:83], v[204:205]
	global_store_dwordx4 v156, v[84:87], s[50:51] offset:512
	global_store_dwordx4 v156, v[80:83], s[50:51] offset:528
	global_load_dwordx4 v[198:201], v156, s[48:49] offset:512
	global_load_dwordx4 v[202:205], v156, s[48:49] offset:528
	s_waitcnt vmcnt(20)
	v_pk_add_f32 v[76:77], v[76:77], v[158:159]
	v_pk_add_f32 v[78:79], v[78:79], v[160:161]
	v_pk_add_f32 v[72:73], v[72:73], v[162:163]
	v_pk_add_f32 v[74:75], v[74:75], v[164:165]
	s_add_u32 s50, s50, 0x10000
	s_addc_u32 s51, s51, 0
	global_store_dwordx4 v156, v[76:79], s[50:51]
	global_store_dwordx4 v156, v[72:75], s[50:51] offset:16
	s_add_u32 s48, s48, 0x10000
	s_addc_u32 s49, s49, 0
	global_load_dwordx4 v[158:161], v156, s[48:49]
	global_load_dwordx4 v[162:165], v156, s[48:49] offset:16
	s_waitcnt vmcnt(20)
	v_pk_add_f32 v[68:69], v[68:69], v[166:167]
	v_pk_add_f32 v[70:71], v[70:71], v[168:169]
	v_pk_add_f32 v[64:65], v[64:65], v[170:171]
	v_pk_add_f32 v[66:67], v[66:67], v[172:173]
	global_store_dwordx4 v156, v[68:71], s[50:51] offset:512
	global_store_dwordx4 v156, v[64:67], s[50:51] offset:528
	global_load_dwordx4 v[166:169], v156, s[48:49] offset:512
	global_load_dwordx4 v[170:173], v156, s[48:49] offset:528
	s_waitcnt vmcnt(20)
	v_pk_add_f32 v[60:61], v[60:61], v[174:175]
	v_pk_add_f32 v[62:63], v[62:63], v[176:177]
	v_pk_add_f32 v[56:57], v[56:57], v[178:179]
	v_pk_add_f32 v[58:59], v[58:59], v[180:181]
	s_add_u32 s50, s50, 0x50000
	s_addc_u32 s51, s51, 0
	global_store_dwordx4 v156, v[60:63], s[50:51]
	global_store_dwordx4 v156, v[56:59], s[50:51] offset:16
	s_add_u32 s48, s48, 0x10000
	s_addc_u32 s49, s49, 0
	global_load_dwordx4 v[174:177], v156, s[48:49]
	global_load_dwordx4 v[178:181], v156, s[48:49] offset:16
	s_waitcnt vmcnt(20)
	v_pk_add_f32 v[52:53], v[52:53], v[182:183]
	v_pk_add_f32 v[54:55], v[54:55], v[184:185]
	v_pk_add_f32 v[48:49], v[48:49], v[186:187]
	v_pk_add_f32 v[50:51], v[50:51], v[188:189]
	global_store_dwordx4 v156, v[52:55], s[50:51] offset:512
	global_store_dwordx4 v156, v[48:51], s[50:51] offset:528
	global_load_dwordx4 v[182:185], v156, s[48:49] offset:512
	global_load_dwordx4 v[186:189], v156, s[48:49] offset:528
	s_waitcnt vmcnt(20)
	v_pk_add_f32 v[44:45], v[44:45], v[190:191]
	v_pk_add_f32 v[46:47], v[46:47], v[192:193]
	v_pk_add_f32 v[40:41], v[40:41], v[194:195]
	v_pk_add_f32 v[42:43], v[42:43], v[196:197]
	s_add_u32 s50, s50, 0x10000
	s_addc_u32 s51, s51, 0
	global_store_dwordx4 v156, v[44:47], s[50:51]
	global_store_dwordx4 v156, v[40:43], s[50:51] offset:16
	s_waitcnt vmcnt(18)
	v_pk_add_f32 v[36:37], v[36:37], v[198:199]
	v_pk_add_f32 v[38:39], v[38:39], v[200:201]
	v_pk_add_f32 v[32:33], v[32:33], v[202:203]
	v_pk_add_f32 v[34:35], v[34:35], v[204:205]
	global_store_dwordx4 v156, v[36:39], s[50:51] offset:512
	global_store_dwordx4 v156, v[32:35], s[50:51] offset:528
	s_waitcnt vmcnt(16)
	v_pk_add_f32 v[28:29], v[28:29], v[158:159]
	v_pk_add_f32 v[30:31], v[30:31], v[160:161]
	v_pk_add_f32 v[24:25], v[24:25], v[162:163]
	v_pk_add_f32 v[26:27], v[26:27], v[164:165]
	s_add_u32 s50, s50, 0x10000
	s_addc_u32 s51, s51, 0
	global_store_dwordx4 v156, v[28:31], s[50:51]
	global_store_dwordx4 v156, v[24:27], s[50:51] offset:16
	s_waitcnt vmcnt(14)
	v_pk_add_f32 v[20:21], v[20:21], v[166:167]
	v_pk_add_f32 v[22:23], v[22:23], v[168:169]
	v_pk_add_f32 v[16:17], v[16:17], v[170:171]
	v_pk_add_f32 v[18:19], v[18:19], v[172:173]
	global_store_dwordx4 v156, v[20:23], s[50:51] offset:512
	global_store_dwordx4 v156, v[16:19], s[50:51] offset:528
	s_waitcnt vmcnt(12)
	v_pk_add_f32 v[12:13], v[12:13], v[174:175]
	v_pk_add_f32 v[14:15], v[14:15], v[176:177]
	v_pk_add_f32 v[8:9], v[8:9], v[178:179]
	v_pk_add_f32 v[10:11], v[10:11], v[180:181]
	s_add_u32 s50, s50, 0x10000
	s_addc_u32 s51, s51, 0
	global_store_dwordx4 v156, v[12:15], s[50:51]
	global_store_dwordx4 v156, v[8:11], s[50:51] offset:16
	s_waitcnt vmcnt(10)
	v_pk_add_f32 v[4:5], v[4:5], v[182:183]
	v_pk_add_f32 v[6:7], v[6:7], v[184:185]
	v_pk_add_f32 v[0:1], v[0:1], v[186:187]
	v_pk_add_f32 v[2:3], v[2:3], v[188:189]
	global_store_dwordx4 v156, v[4:7], s[50:51] offset:512
	global_store_dwordx4 v156, v[0:3], s[50:51] offset:528
	s_cbranch_vccnz .LBB0_852
	s_andn2_b64 vcc, exec, s[12:13]
	s_cbranch_vccnz .LBB0_851
	s_barrier
	s_branch .LBB0_851

.LBB0_1545:
	v_lshl_add_u32 v140, s44, 8, v142
	v_lshl_or_b32 v138, s67, 8, v144
	v_lshlrev_b32_e32 v157, 2, v138
	v_lshl_add_u32 v156, v140, 12, v157
	s_mov_b64 s[46:47], s[12:13]
	s_mov_b64 s[48:49], s[12:13]
	s_mov_b64 s[4:5], -1
	s_andn2_b64 vcc, exec, s[6:7]
	global_load_dwordx4 v[158:161], v156, s[46:47]
	global_load_dwordx4 v[162:165], v156, s[46:47] offset:16
	global_load_dwordx4 v[166:169], v156, s[46:47] offset:512
	global_load_dwordx4 v[170:173], v156, s[46:47] offset:528
	s_add_u32 s46, s46, 0x10000
	s_addc_u32 s47, s47, 0
	global_load_dwordx4 v[174:177], v156, s[46:47]
	global_load_dwordx4 v[178:181], v156, s[46:47] offset:16
	global_load_dwordx4 v[182:185], v156, s[46:47] offset:512
	global_load_dwordx4 v[186:189], v156, s[46:47] offset:528
	s_add_u32 s46, s46, 0x10000
	s_addc_u32 s47, s47, 0
	global_load_dwordx4 v[190:193], v156, s[46:47]
	global_load_dwordx4 v[194:197], v156, s[46:47] offset:16
	global_load_dwordx4 v[198:201], v156, s[46:47] offset:512
	global_load_dwordx4 v[202:205], v156, s[46:47] offset:528
	s_waitcnt vmcnt(10)
	v_pk_add_f32 v[124:125], v[124:125], v[158:159]
	v_pk_add_f32 v[126:127], v[126:127], v[160:161]
	v_pk_add_f32 v[120:121], v[120:121], v[162:163]
	v_pk_add_f32 v[122:123], v[122:123], v[164:165]
	global_store_dwordx4 v156, v[124:127], s[48:49]
	global_store_dwordx4 v156, v[120:123], s[48:49] offset:16
	s_add_u32 s46, s46, 0x10000
	s_addc_u32 s47, s47, 0
	global_load_dwordx4 v[158:161], v156, s[46:47]
	global_load_dwordx4 v[162:165], v156, s[46:47] offset:16
	s_waitcnt vmcnt(12)
	v_pk_add_f32 v[116:117], v[116:117], v[166:167]
	v_pk_add_f32 v[118:119], v[118:119], v[168:169]
	v_pk_add_f32 v[112:113], v[112:113], v[170:171]
	v_pk_add_f32 v[114:115], v[114:115], v[172:173]
	global_store_dwordx4 v156, v[116:119], s[48:49] offset:512
	global_store_dwordx4 v156, v[112:115], s[48:49] offset:528
	global_load_dwordx4 v[166:169], v156, s[46:47] offset:512
	global_load_dwordx4 v[170:173], v156, s[46:47] offset:528
	s_waitcnt vmcnt(14)
	v_pk_add_f32 v[108:109], v[108:109], v[174:175]
	v_pk_add_f32 v[110:111], v[110:111], v[176:177]
	v_pk_add_f32 v[104:105], v[104:105], v[178:179]
	v_pk_add_f32 v[106:107], v[106:107], v[180:181]
	s_add_u32 s48, s48, 0x10000
	s_addc_u32 s49, s49, 0
	global_store_dwordx4 v156, v[108:111], s[48:49]
	global_store_dwordx4 v156, v[104:107], s[48:49] offset:16
	s_add_u32 s46, s46, 0x50000
	s_addc_u32 s47, s47, 0
	global_load_dwordx4 v[174:177], v156, s[46:47]
	global_load_dwordx4 v[178:181], v156, s[46:47] offset:16
	s_waitcnt vmcnt(16)
	v_pk_add_f32 v[100:101], v[100:101], v[182:183]
	v_pk_add_f32 v[102:103], v[102:103], v[184:185]
	v_pk_add_f32 v[96:97], v[96:97], v[186:187]
	v_pk_add_f32 v[98:99], v[98:99], v[188:189]
	global_store_dwordx4 v156, v[100:103], s[48:49] offset:512
	global_store_dwordx4 v156, v[96:99], s[48:49] offset:528
	global_load_dwordx4 v[182:185], v156, s[46:47] offset:512
	global_load_dwordx4 v[186:189], v156, s[46:47] offset:528
	s_waitcnt vmcnt(18)
	v_pk_add_f32 v[92:93], v[92:93], v[190:191]
	v_pk_add_f32 v[94:95], v[94:95], v[192:193]
	v_pk_add_f32 v[88:89], v[88:89], v[194:195]
	v_pk_add_f32 v[90:91], v[90:91], v[196:197]
	s_add_u32 s48, s48, 0x10000
	s_addc_u32 s49, s49, 0
	global_store_dwordx4 v156, v[92:95], s[48:49]
	global_store_dwordx4 v156, v[88:91], s[48:49] offset:16
	s_add_u32 s46, s46, 0x10000
	s_addc_u32 s47, s47, 0
	global_load_dwordx4 v[190:193], v156, s[46:47]
	global_load_dwordx4 v[194:197], v156, s[46:47] offset:16
	s_waitcnt vmcnt(20)
	v_pk_add_f32 v[84:85], v[84:85], v[198:199]
	v_pk_add_f32 v[86:87], v[86:87], v[200:201]
	v_pk_add_f32 v[80:81], v[80:81], v[202:203]
	v_pk_add_f32 v[82:83], v[82:83], v[204:205]
	global_store_dwordx4 v156, v[84:87], s[48:49] offset:512
	global_store_dwordx4 v156, v[80:83], s[48:49] offset:528
	global_load_dwordx4 v[198:201], v156, s[46:47] offset:512
	global_load_dwordx4 v[202:205], v156, s[46:47] offset:528
	s_waitcnt vmcnt(20)
	v_pk_add_f32 v[76:77], v[76:77], v[158:159]
	v_pk_add_f32 v[78:79], v[78:79], v[160:161]
	v_pk_add_f32 v[72:73], v[72:73], v[162:163]
	v_pk_add_f32 v[74:75], v[74:75], v[164:165]
	s_add_u32 s48, s48, 0x10000
	s_addc_u32 s49, s49, 0
	global_store_dwordx4 v156, v[76:79], s[48:49]
	global_store_dwordx4 v156, v[72:75], s[48:49] offset:16
	s_add_u32 s46, s46, 0x10000
	s_addc_u32 s47, s47, 0
	global_load_dwordx4 v[158:161], v156, s[46:47]
	global_load_dwordx4 v[162:165], v156, s[46:47] offset:16
	s_waitcnt vmcnt(20)
	v_pk_add_f32 v[68:69], v[68:69], v[166:167]
	v_pk_add_f32 v[70:71], v[70:71], v[168:169]
	v_pk_add_f32 v[64:65], v[64:65], v[170:171]
	v_pk_add_f32 v[66:67], v[66:67], v[172:173]
	global_store_dwordx4 v156, v[68:71], s[48:49] offset:512
	global_store_dwordx4 v156, v[64:67], s[48:49] offset:528
	global_load_dwordx4 v[166:169], v156, s[46:47] offset:512
	global_load_dwordx4 v[170:173], v156, s[46:47] offset:528
	s_waitcnt vmcnt(20)
	v_pk_add_f32 v[60:61], v[60:61], v[174:175]
	v_pk_add_f32 v[62:63], v[62:63], v[176:177]
	v_pk_add_f32 v[56:57], v[56:57], v[178:179]
	v_pk_add_f32 v[58:59], v[58:59], v[180:181]
	s_add_u32 s48, s48, 0x50000
	s_addc_u32 s49, s49, 0
	global_store_dwordx4 v156, v[60:63], s[48:49]
	global_store_dwordx4 v156, v[56:59], s[48:49] offset:16
	s_add_u32 s46, s46, 0x10000
	s_addc_u32 s47, s47, 0
	global_load_dwordx4 v[174:177], v156, s[46:47]
	global_load_dwordx4 v[178:181], v156, s[46:47] offset:16
	s_waitcnt vmcnt(20)
	v_pk_add_f32 v[52:53], v[52:53], v[182:183]
	v_pk_add_f32 v[54:55], v[54:55], v[184:185]
	v_pk_add_f32 v[48:49], v[48:49], v[186:187]
	v_pk_add_f32 v[50:51], v[50:51], v[188:189]
	global_store_dwordx4 v156, v[52:55], s[48:49] offset:512
	global_store_dwordx4 v156, v[48:51], s[48:49] offset:528
	global_load_dwordx4 v[182:185], v156, s[46:47] offset:512
	global_load_dwordx4 v[186:189], v156, s[46:47] offset:528
	s_waitcnt vmcnt(20)
	v_pk_add_f32 v[44:45], v[44:45], v[190:191]
	v_pk_add_f32 v[46:47], v[46:47], v[192:193]
	v_pk_add_f32 v[40:41], v[40:41], v[194:195]
	v_pk_add_f32 v[42:43], v[42:43], v[196:197]
	s_add_u32 s48, s48, 0x10000
	s_addc_u32 s49, s49, 0
	global_store_dwordx4 v156, v[44:47], s[48:49]
	global_store_dwordx4 v156, v[40:43], s[48:49] offset:16
	s_waitcnt vmcnt(18)
	v_pk_add_f32 v[36:37], v[36:37], v[198:199]
	v_pk_add_f32 v[38:39], v[38:39], v[200:201]
	v_pk_add_f32 v[32:33], v[32:33], v[202:203]
	v_pk_add_f32 v[34:35], v[34:35], v[204:205]
	global_store_dwordx4 v156, v[36:39], s[48:49] offset:512
	global_store_dwordx4 v156, v[32:35], s[48:49] offset:528
	s_waitcnt vmcnt(16)
	v_pk_add_f32 v[28:29], v[28:29], v[158:159]
	v_pk_add_f32 v[30:31], v[30:31], v[160:161]
	v_pk_add_f32 v[24:25], v[24:25], v[162:163]
	v_pk_add_f32 v[26:27], v[26:27], v[164:165]
	s_add_u32 s48, s48, 0x10000
	s_addc_u32 s49, s49, 0
	global_store_dwordx4 v156, v[28:31], s[48:49]
	global_store_dwordx4 v156, v[24:27], s[48:49] offset:16
	s_waitcnt vmcnt(14)
	v_pk_add_f32 v[20:21], v[20:21], v[166:167]
	v_pk_add_f32 v[22:23], v[22:23], v[168:169]
	v_pk_add_f32 v[16:17], v[16:17], v[170:171]
	v_pk_add_f32 v[18:19], v[18:19], v[172:173]
	global_store_dwordx4 v156, v[20:23], s[48:49] offset:512
	global_store_dwordx4 v156, v[16:19], s[48:49] offset:528
	s_waitcnt vmcnt(12)
	v_pk_add_f32 v[12:13], v[12:13], v[174:175]
	v_pk_add_f32 v[14:15], v[14:15], v[176:177]
	v_pk_add_f32 v[8:9], v[8:9], v[178:179]
	v_pk_add_f32 v[10:11], v[10:11], v[180:181]
	s_add_u32 s48, s48, 0x10000
	s_addc_u32 s49, s49, 0
	global_store_dwordx4 v156, v[12:15], s[48:49]
	global_store_dwordx4 v156, v[8:11], s[48:49] offset:16
	s_waitcnt vmcnt(10)
	v_pk_add_f32 v[4:5], v[4:5], v[182:183]
	v_pk_add_f32 v[6:7], v[6:7], v[184:185]
	v_pk_add_f32 v[0:1], v[0:1], v[186:187]
	v_pk_add_f32 v[2:3], v[2:3], v[188:189]
	global_store_dwordx4 v156, v[4:7], s[48:49] offset:512
	global_store_dwordx4 v156, v[0:3], s[48:49] offset:528
	s_cbranch_vccnz .LBB0_1534
	s_andn2_b64 vcc, exec, s[10:11]
	s_cbranch_vccnz .LBB0_1533
	s_barrier
	s_branch .LBB0_1533

.LBB0_1805:
	v_lshl_add_u32 v140, s70, 8, v142
	v_lshl_or_b32 v138, s71, 8, v144
	v_lshlrev_b32_e32 v157, 2, v138
	v_lshl_add_u32 v156, v140, 12, v157
	s_mov_b64 s[42:43], s[28:29]
	s_mov_b64 s[44:45], s[14:15]
	s_and_b64 vcc, exec, s[6:7]
	s_mov_b64 s[4:5], -1
	global_load_dwordx4 v[158:161], v156, s[42:43]
	global_load_dwordx4 v[162:165], v156, s[42:43] offset:16
	global_load_dwordx4 v[166:169], v156, s[42:43] offset:512
	global_load_dwordx4 v[170:173], v156, s[42:43] offset:528
	s_add_u32 s42, s42, 0x10000
	s_addc_u32 s43, s43, 0
	global_load_dwordx4 v[174:177], v156, s[42:43]
	global_load_dwordx4 v[178:181], v156, s[42:43] offset:16
	global_load_dwordx4 v[182:185], v156, s[42:43] offset:512
	global_load_dwordx4 v[186:189], v156, s[42:43] offset:528
	s_add_u32 s42, s42, 0x10000
	s_addc_u32 s43, s43, 0
	global_load_dwordx4 v[190:193], v156, s[42:43]
	global_load_dwordx4 v[194:197], v156, s[42:43] offset:16
	global_load_dwordx4 v[198:201], v156, s[42:43] offset:512
	global_load_dwordx4 v[202:205], v156, s[42:43] offset:528
	s_waitcnt vmcnt(10)
	v_pk_add_f32 v[124:125], v[124:125], v[158:159]
	v_pk_add_f32 v[126:127], v[126:127], v[160:161]
	v_pk_add_f32 v[120:121], v[120:121], v[162:163]
	v_pk_add_f32 v[122:123], v[122:123], v[164:165]
	global_store_dwordx4 v156, v[124:127], s[44:45]
	global_store_dwordx4 v156, v[120:123], s[44:45] offset:16
	s_add_u32 s42, s42, 0x10000
	s_addc_u32 s43, s43, 0
	global_load_dwordx4 v[158:161], v156, s[42:43]
	global_load_dwordx4 v[162:165], v156, s[42:43] offset:16
	s_waitcnt vmcnt(12)
	v_pk_add_f32 v[112:113], v[112:113], v[166:167]
	v_pk_add_f32 v[114:115], v[114:115], v[168:169]
	v_pk_add_f32 v[108:109], v[108:109], v[170:171]
	v_pk_add_f32 v[110:111], v[110:111], v[172:173]
	global_store_dwordx4 v156, v[112:115], s[44:45] offset:512
	global_store_dwordx4 v156, v[108:111], s[44:45] offset:528
	global_load_dwordx4 v[166:169], v156, s[42:43] offset:512
	global_load_dwordx4 v[170:173], v156, s[42:43] offset:528
	s_waitcnt vmcnt(14)
	v_pk_add_f32 v[116:117], v[116:117], v[174:175]
	v_pk_add_f32 v[118:119], v[118:119], v[176:177]
	v_pk_add_f32 v[104:105], v[104:105], v[178:179]
	v_pk_add_f32 v[106:107], v[106:107], v[180:181]
	s_add_u32 s44, s44, 0x10000
	s_addc_u32 s45, s45, 0
	global_store_dwordx4 v156, v[116:119], s[44:45]
	global_store_dwordx4 v156, v[104:107], s[44:45] offset:16
	s_add_u32 s42, s42, 0x50000
	s_addc_u32 s43, s43, 0
	global_load_dwordx4 v[174:177], v156, s[42:43]
	global_load_dwordx4 v[178:181], v156, s[42:43] offset:16
	s_waitcnt vmcnt(16)
	v_pk_add_f32 v[96:97], v[96:97], v[182:183]
	v_pk_add_f32 v[98:99], v[98:99], v[184:185]
	v_pk_add_f32 v[92:93], v[92:93], v[186:187]
	v_pk_add_f32 v[94:95], v[94:95], v[188:189]
	global_store_dwordx4 v156, v[96:99], s[44:45] offset:512
	global_store_dwordx4 v156, v[92:95], s[44:45] offset:528
	global_load_dwordx4 v[182:185], v156, s[42:43] offset:512
	global_load_dwordx4 v[186:189], v156, s[42:43] offset:528
	s_waitcnt vmcnt(18)
	v_pk_add_f32 v[100:101], v[100:101], v[190:191]
	v_pk_add_f32 v[102:103], v[102:103], v[192:193]
	v_pk_add_f32 v[88:89], v[88:89], v[194:195]
	v_pk_add_f32 v[90:91], v[90:91], v[196:197]
	s_add_u32 s44, s44, 0x10000
	s_addc_u32 s45, s45, 0
	global_store_dwordx4 v156, v[100:103], s[44:45]
	global_store_dwordx4 v156, v[88:91], s[44:45] offset:16
	s_add_u32 s42, s42, 0x10000
	s_addc_u32 s43, s43, 0
	global_load_dwordx4 v[190:193], v156, s[42:43]
	global_load_dwordx4 v[194:197], v156, s[42:43] offset:16
	s_waitcnt vmcnt(20)
	v_pk_add_f32 v[80:81], v[80:81], v[198:199]
	v_pk_add_f32 v[82:83], v[82:83], v[200:201]
	v_pk_add_f32 v[76:77], v[76:77], v[202:203]
	v_pk_add_f32 v[78:79], v[78:79], v[204:205]
	global_store_dwordx4 v156, v[80:83], s[44:45] offset:512
	global_store_dwordx4 v156, v[76:79], s[44:45] offset:528
	global_load_dwordx4 v[198:201], v156, s[42:43] offset:512
	global_load_dwordx4 v[202:205], v156, s[42:43] offset:528
	s_waitcnt vmcnt(20)
	v_pk_add_f32 v[84:85], v[84:85], v[158:159]
	v_pk_add_f32 v[86:87], v[86:87], v[160:161]
	v_pk_add_f32 v[72:73], v[72:73], v[162:163]
	v_pk_add_f32 v[74:75], v[74:75], v[164:165]
	s_add_u32 s44, s44, 0x10000
	s_addc_u32 s45, s45, 0
	global_store_dwordx4 v156, v[84:87], s[44:45]
	global_store_dwordx4 v156, v[72:75], s[44:45] offset:16
	s_add_u32 s42, s42, 0x10000
	s_addc_u32 s43, s43, 0
	global_load_dwordx4 v[158:161], v156, s[42:43]
	global_load_dwordx4 v[162:165], v156, s[42:43] offset:16
	s_waitcnt vmcnt(20)
	v_pk_add_f32 v[68:69], v[68:69], v[166:167]
	v_pk_add_f32 v[70:71], v[70:71], v[168:169]
	v_pk_add_f32 v[64:65], v[64:65], v[170:171]
	v_pk_add_f32 v[66:67], v[66:67], v[172:173]
	global_store_dwordx4 v156, v[68:71], s[44:45] offset:512
	global_store_dwordx4 v156, v[64:67], s[44:45] offset:528
	global_load_dwordx4 v[166:169], v156, s[42:43] offset:512
	global_load_dwordx4 v[170:173], v156, s[42:43] offset:528
	s_waitcnt vmcnt(20)
	v_pk_add_f32 v[60:61], v[60:61], v[174:175]
	v_pk_add_f32 v[62:63], v[62:63], v[176:177]
	v_pk_add_f32 v[56:57], v[56:57], v[178:179]
	v_pk_add_f32 v[58:59], v[58:59], v[180:181]
	s_add_u32 s44, s44, 0x50000
	s_addc_u32 s45, s45, 0
	global_store_dwordx4 v156, v[60:63], s[44:45]
	global_store_dwordx4 v156, v[56:59], s[44:45] offset:16
	s_add_u32 s42, s42, 0x10000
	s_addc_u32 s43, s43, 0
	global_load_dwordx4 v[174:177], v156, s[42:43]
	global_load_dwordx4 v[178:181], v156, s[42:43] offset:16
	s_waitcnt vmcnt(20)
	v_pk_add_f32 v[48:49], v[48:49], v[182:183]
	v_pk_add_f32 v[50:51], v[50:51], v[184:185]
	v_pk_add_f32 v[44:45], v[44:45], v[186:187]
	v_pk_add_f32 v[46:47], v[46:47], v[188:189]
	global_store_dwordx4 v156, v[48:51], s[44:45] offset:512
	global_store_dwordx4 v156, v[44:47], s[44:45] offset:528
	global_load_dwordx4 v[182:185], v156, s[42:43] offset:512
	global_load_dwordx4 v[186:189], v156, s[42:43] offset:528
	s_waitcnt vmcnt(20)
	v_pk_add_f32 v[52:53], v[52:53], v[190:191]
	v_pk_add_f32 v[54:55], v[54:55], v[192:193]
	v_pk_add_f32 v[40:41], v[40:41], v[194:195]
	v_pk_add_f32 v[42:43], v[42:43], v[196:197]
	s_add_u32 s44, s44, 0x10000
	s_addc_u32 s45, s45, 0
	global_store_dwordx4 v156, v[52:55], s[44:45]
	global_store_dwordx4 v156, v[40:43], s[44:45] offset:16
	s_waitcnt vmcnt(18)
	v_pk_add_f32 v[32:33], v[32:33], v[198:199]
	v_pk_add_f32 v[34:35], v[34:35], v[200:201]
	v_pk_add_f32 v[28:29], v[28:29], v[202:203]
	v_pk_add_f32 v[30:31], v[30:31], v[204:205]
	global_store_dwordx4 v156, v[32:35], s[44:45] offset:512
	global_store_dwordx4 v156, v[28:31], s[44:45] offset:528
	s_waitcnt vmcnt(16)
	v_pk_add_f32 v[36:37], v[36:37], v[158:159]
	v_pk_add_f32 v[38:39], v[38:39], v[160:161]
	v_pk_add_f32 v[24:25], v[24:25], v[162:163]
	v_pk_add_f32 v[26:27], v[26:27], v[164:165]
	s_add_u32 s44, s44, 0x10000
	s_addc_u32 s45, s45, 0
	global_store_dwordx4 v156, v[36:39], s[44:45]
	global_store_dwordx4 v156, v[24:27], s[44:45] offset:16
	s_waitcnt vmcnt(14)
	v_pk_add_f32 v[16:17], v[16:17], v[166:167]
	v_pk_add_f32 v[18:19], v[18:19], v[168:169]
	v_pk_add_f32 v[12:13], v[12:13], v[170:171]
	v_pk_add_f32 v[14:15], v[14:15], v[172:173]
	global_store_dwordx4 v156, v[16:19], s[44:45] offset:512
	global_store_dwordx4 v156, v[12:15], s[44:45] offset:528
	s_waitcnt vmcnt(12)
	v_pk_add_f32 v[20:21], v[20:21], v[174:175]
	v_pk_add_f32 v[22:23], v[22:23], v[176:177]
	v_pk_add_f32 v[8:9], v[8:9], v[178:179]
	v_pk_add_f32 v[10:11], v[10:11], v[180:181]
	s_add_u32 s44, s44, 0x10000
	s_addc_u32 s45, s45, 0
	global_store_dwordx4 v156, v[20:23], s[44:45]
	global_store_dwordx4 v156, v[8:11], s[44:45] offset:16
	s_waitcnt vmcnt(10)
	v_pk_add_f32 v[4:5], v[4:5], v[182:183]
	v_pk_add_f32 v[6:7], v[6:7], v[184:185]
	v_pk_add_f32 v[0:1], v[0:1], v[186:187]
	v_pk_add_f32 v[2:3], v[2:3], v[188:189]
	global_store_dwordx4 v156, v[4:7], s[44:45] offset:512
	global_store_dwordx4 v156, v[0:3], s[44:45] offset:528
	s_cbranch_vccnz .LBB0_1790
	s_andn2_b64 vcc, exec, s[0:1]
	s_cbranch_vccnz .LBB0_1789
	s_barrier
	s_branch .LBB0_1789
